# P3 sample-sequence units: both FIN loads of a segment iteration issued together (one exposed latency per iteration instead of two)
# baseline (speedup 1.0000x reference)
; __device__ __forceinline__ void ret_phase(const Params& P, LAS unsigned char* lds, int tid, int lane, int wave, int bid, int G) {
;     ...
; #pragma unroll
;                 for (int jj = 0; jj < 2; ++jj) { const u32x4 rf = *(const u32x4*)(F + 16 * (tid + 512 * jj)); const u32x4 f0 = fp8x8_to_bf16x8(rf.x, rf.y), f1 = fp8x8_to_bf16x8(rf.z, rf.w);
;                     ST_FMA(sfr[2 * jj], f0, wgt); ST_FMA(sfr[2 * jj + 1], f1, wgt); }
;                 wgt *= df32; }
.LBB0_387:
	s_lshl_b64 s[0:1], s[18:19], 16
	v_lshlrev_b32_e32 v144, 16, v70
	v_and_b32_e32 v145, 0xffff0000, v70
	v_lshlrev_b32_e32 v146, 16, v71
	v_and_b32_e32 v147, 0xffff0000, v71
	v_lshl_add_u64 v[70:71], v[120:121], 0, s[0:1]
	v_lshlrev_b32_e32 v119, 16, v66
	v_and_b32_e32 v135, 0xffff0000, v66
	v_lshlrev_b32_e32 v138, 16, v67
	v_and_b32_e32 v139, 0xffff0000, v67
	v_lshlrev_b32_e32 v140, 16, v68
	v_and_b32_e32 v141, 0xffff0000, v68
	v_lshlrev_b32_e32 v142, 16, v69
	v_and_b32_e32 v143, 0xffff0000, v69
	global_load_dwordx4 v[66:69], v[70:71], off
	v_add_co_u32_e32 v100, vcc, s49, v70
	v_lshlrev_b32_e32 v148, 16, v72
	v_and_b32_e32 v149, 0xffff0000, v72
	v_lshlrev_b32_e32 v150, 16, v73
	v_and_b32_e32 v151, 0xffff0000, v73
	v_addc_co_u32_e32 v101, vcc, 0, v71, vcc
	global_load_dwordx4 v[220:223], v[100:101], off
	s_add_i32 s18, s18, -4
	s_add_i32 s35, s35, -1
	s_cmp_lt_u32 s35, 2
	s_waitcnt vmcnt(1)
	v_cvt_pk_f32_fp8_e32 v[70:71], v66
	v_cvt_pk_f32_fp8_sdwa v[72:73], v66 src0_sel:WORD_1
	v_cvt_pk_f32_fp8_e32 v[102:103], v67
	v_cvt_pk_f32_fp8_sdwa v[66:67], v67 src0_sel:WORD_1
	v_cvt_pk_f32_fp8_e32 v[122:123], v68
	v_cvt_pk_f32_fp8_sdwa v[124:125], v68 src0_sel:WORD_1
	v_cvt_pk_f32_fp8_e32 v[136:137], v69
	v_cvt_pk_f32_fp8_sdwa v[68:69], v69 src0_sel:WORD_1
	v_cvt_pk_bf16_f32 v70, v70, v71
	v_cvt_pk_bf16_f32 v71, v72, v73
	v_cvt_pk_bf16_f32 v72, v102, v103
	v_cvt_pk_bf16_f32 v66, v66, v67
	v_cvt_pk_bf16_f32 v67, v122, v123
	v_cvt_pk_bf16_f32 v73, v124, v125
	v_cvt_pk_bf16_f32 v102, v136, v137
	v_cvt_pk_bf16_f32 v68, v68, v69
	s_nop 0
	v_lshlrev_b32_e32 v69, 16, v70
	v_and_b32_e32 v70, 0xffff0000, v70
	v_lshlrev_b32_e32 v103, 16, v71
	v_and_b32_e32 v71, 0xffff0000, v71
	v_lshlrev_b32_e32 v122, 16, v72
	v_and_b32_e32 v72, 0xffff0000, v72
	v_lshlrev_b32_e32 v123, 16, v66
	v_and_b32_e32 v66, 0xffff0000, v66
	v_lshlrev_b32_e32 v124, 16, v67
	v_and_b32_e32 v67, 0xffff0000, v67
	v_lshlrev_b32_e32 v125, 16, v73
	v_and_b32_e32 v73, 0xffff0000, v73
	v_lshlrev_b32_e32 v136, 16, v102
	v_and_b32_e32 v102, 0xffff0000, v102
	v_lshlrev_b32_e32 v137, 16, v68
	v_and_b32_e32 v68, 0xffff0000, v68
	v_fmac_f32_e32 v119, v99, v69
	v_fmac_f32_e32 v135, v99, v70
	v_fmac_f32_e32 v138, v99, v103
	v_fmac_f32_e32 v139, v99, v71
	v_fmac_f32_e32 v140, v99, v122
	v_fmac_f32_e32 v141, v99, v72
	v_fmac_f32_e32 v142, v99, v123
	v_fmac_f32_e32 v143, v99, v66
	v_fmac_f32_e32 v144, v99, v124
	v_fmac_f32_e32 v145, v99, v67
	v_fmac_f32_e32 v146, v99, v125
	v_fmac_f32_e32 v147, v99, v73
	v_fmac_f32_e32 v148, v99, v136
	v_fmac_f32_e32 v149, v99, v102
	v_fmac_f32_e32 v150, v99, v137
	v_fmac_f32_e32 v151, v99, v68
	v_cvt_pk_bf16_f32 v66, v119, v135
	v_cvt_pk_bf16_f32 v67, v138, v139
	v_cvt_pk_bf16_f32 v68, v140, v141
	v_cvt_pk_bf16_f32 v69, v142, v143
	v_cvt_pk_bf16_f32 v70, v144, v145
	v_cvt_pk_bf16_f32 v71, v146, v147
	v_cvt_pk_bf16_f32 v72, v148, v149
	v_cvt_pk_bf16_f32 v73, v150, v151
	s_waitcnt vmcnt(0)
	v_mov_b32_e32 v100, v220
	v_mov_b32_e32 v101, v221
	v_mov_b32_e32 v102, v222
	v_mov_b32_e32 v103, v223
	v_lshlrev_b32_e32 v119, 16, v82
	v_and_b32_e32 v135, 0xffff0000, v82
	v_lshlrev_b32_e32 v136, 16, v83
	v_and_b32_e32 v137, 0xffff0000, v83
	v_lshlrev_b32_e32 v138, 16, v84
	v_and_b32_e32 v139, 0xffff0000, v84
	v_lshlrev_b32_e32 v140, 16, v85
	v_and_b32_e32 v141, 0xffff0000, v85
	v_lshlrev_b32_e32 v142, 16, v86
	v_and_b32_e32 v143, 0xffff0000, v86
	v_lshlrev_b32_e32 v144, 16, v87
	v_and_b32_e32 v145, 0xffff0000, v87
	v_lshlrev_b32_e32 v146, 16, v88
	v_and_b32_e32 v147, 0xffff0000, v88
	v_lshlrev_b32_e32 v148, 16, v89
	v_and_b32_e32 v149, 0xffff0000, v89
	s_waitcnt vmcnt(0)
	v_cvt_pk_f32_fp8_e32 v[82:83], v100
	v_cvt_pk_f32_fp8_sdwa v[84:85], v100 src0_sel:WORD_1
	v_cvt_pk_f32_fp8_e32 v[86:87], v101
	v_cvt_pk_f32_fp8_sdwa v[88:89], v101 src0_sel:WORD_1
	v_cvt_pk_f32_fp8_e32 v[100:101], v102
	v_cvt_pk_f32_fp8_sdwa v[122:123], v102 src0_sel:WORD_1
	v_cvt_pk_f32_fp8_e32 v[124:125], v103
	v_cvt_pk_f32_fp8_sdwa v[102:103], v103 src0_sel:WORD_1
	v_cvt_pk_bf16_f32 v82, v82, v83
	v_cvt_pk_bf16_f32 v83, v84, v85
	v_cvt_pk_bf16_f32 v84, v86, v87
	v_cvt_pk_bf16_f32 v85, v88, v89
	v_cvt_pk_bf16_f32 v86, v100, v101
	v_cvt_pk_bf16_f32 v87, v122, v123
	v_cvt_pk_bf16_f32 v88, v124, v125
	v_cvt_pk_bf16_f32 v89, v102, v103
	s_nop 0
	v_lshlrev_b32_e32 v100, 16, v82
	v_and_b32_e32 v82, 0xffff0000, v82
	v_lshlrev_b32_e32 v101, 16, v83
	v_and_b32_e32 v83, 0xffff0000, v83
	v_lshlrev_b32_e32 v102, 16, v84
	v_and_b32_e32 v84, 0xffff0000, v84
	v_lshlrev_b32_e32 v103, 16, v85
	v_and_b32_e32 v85, 0xffff0000, v85
	v_lshlrev_b32_e32 v122, 16, v86
	v_and_b32_e32 v86, 0xffff0000, v86
	v_lshlrev_b32_e32 v123, 16, v87
	v_and_b32_e32 v87, 0xffff0000, v87
	v_lshlrev_b32_e32 v124, 16, v88
	v_and_b32_e32 v88, 0xffff0000, v88
	v_lshlrev_b32_e32 v125, 16, v89
	v_and_b32_e32 v89, 0xffff0000, v89
	v_fmac_f32_e32 v119, v99, v100
	v_fmac_f32_e32 v135, v99, v82
	v_fmac_f32_e32 v136, v99, v101
	v_fmac_f32_e32 v137, v99, v83
	v_fmac_f32_e32 v138, v99, v102
	v_fmac_f32_e32 v139, v99, v84
	v_fmac_f32_e32 v140, v99, v103
	v_fmac_f32_e32 v141, v99, v85
	v_fmac_f32_e32 v142, v99, v122
	v_fmac_f32_e32 v143, v99, v86
	v_fmac_f32_e32 v144, v99, v123
	v_fmac_f32_e32 v145, v99, v87
	v_fmac_f32_e32 v146, v99, v124
	v_fmac_f32_e32 v147, v99, v88
	v_fmac_f32_e32 v148, v99, v125
	v_fmac_f32_e32 v149, v99, v89
	v_mul_f32_e32 v99, v98, v99
	v_cvt_pk_bf16_f32 v82, v119, v135
	v_cvt_pk_bf16_f32 v83, v136, v137
	v_cvt_pk_bf16_f32 v84, v138, v139
	v_cvt_pk_bf16_f32 v85, v140, v141
	v_cvt_pk_bf16_f32 v86, v142, v143
	v_cvt_pk_bf16_f32 v87, v144, v145
	v_cvt_pk_bf16_f32 v88, v146, v147
	v_cvt_pk_bf16_f32 v89, v148, v149
	s_cbranch_scc0 .LBB0_387

; __device__ __forceinline__ void ret_phase(const Params& P, LAS unsigned char* lds, int tid, int lane, int wave, int bid, int G) {
;     ...
;             for (int i2 = k + 1; i2 < 4; ++i2) { const unsigned char* F = (const unsigned char*)(FIN + ((size_t)((16 + i2) * 4 + h) * 2 + 1) * 16384);
; #pragma unroll
;                 for (int jj = 0; jj < 2; ++jj) { const u32x4 rf = *(const u32x4*)(F + 16 * (tid + 512 * jj)); const u32x4 f0 = fp8x8_to_bf16x8(rf.x, rf.y), f1 = fp8x8_to_bf16x8(rf.z, rf.w);
;                     ST_FMA(sbr[2 * jj], f0, wgt); ST_FMA(sbr[2 * jj + 1], f1, wgt); }
;                 wgt *= db32; }
.LBB0_390:
	s_lshl_b64 s[0:1], s[18:19], 1
	s_add_u32 s0, s16, s0
	s_addc_u32 s1, s17, s1
	v_lshlrev_b32_e32 v119, 16, v74
	v_and_b32_e32 v135, 0xffff0000, v74
	v_lshlrev_b32_e32 v138, 16, v75
	v_and_b32_e32 v139, 0xffff0000, v75
	v_lshl_add_u64 v[74:75], s[0:1], 0, v[116:117]
	v_lshlrev_b32_e32 v140, 16, v76
	v_and_b32_e32 v141, 0xffff0000, v76
	v_add_co_u32_e32 v76, vcc, s47, v74
	v_lshlrev_b32_e32 v142, 16, v77
	v_and_b32_e32 v143, 0xffff0000, v77
	v_addc_co_u32_e32 v77, vcc, 0, v75, vcc
	v_add_co_u32_e32 v100, vcc, s50, v74
	v_lshlrev_b32_e32 v144, 16, v78
	s_nop 0
	v_addc_co_u32_e32 v101, vcc, 0, v75, vcc
	global_load_dwordx4 v[74:77], v[76:77], off
	global_load_dwordx4 v[220:223], v[100:101], off
	v_and_b32_e32 v145, 0xffff0000, v78
	v_lshlrev_b32_e32 v146, 16, v79
	v_and_b32_e32 v147, 0xffff0000, v79
	v_lshlrev_b32_e32 v148, 16, v80
	v_and_b32_e32 v149, 0xffff0000, v80
	v_lshlrev_b32_e32 v150, 16, v81
	v_and_b32_e32 v151, 0xffff0000, v81
	s_add_i32 s18, s18, 0x20000
	s_add_i32 s4, s4, 1
	s_cmp_lt_u32 s4, 2
	s_waitcnt vmcnt(1)
	v_cvt_pk_f32_fp8_e32 v[78:79], v74
	v_cvt_pk_f32_fp8_sdwa v[80:81], v74 src0_sel:WORD_1
	v_cvt_pk_f32_fp8_e32 v[102:103], v75
	v_cvt_pk_f32_fp8_sdwa v[74:75], v75 src0_sel:WORD_1
	v_cvt_pk_f32_fp8_e32 v[122:123], v76
	v_cvt_pk_f32_fp8_sdwa v[124:125], v76 src0_sel:WORD_1
	v_cvt_pk_f32_fp8_e32 v[136:137], v77
	v_cvt_pk_f32_fp8_sdwa v[76:77], v77 src0_sel:WORD_1
	v_cvt_pk_bf16_f32 v78, v78, v79
	v_cvt_pk_bf16_f32 v79, v80, v81
	v_cvt_pk_bf16_f32 v80, v102, v103
	v_cvt_pk_bf16_f32 v74, v74, v75
	v_cvt_pk_bf16_f32 v75, v122, v123
	v_cvt_pk_bf16_f32 v81, v124, v125
	v_cvt_pk_bf16_f32 v102, v136, v137
	v_cvt_pk_bf16_f32 v76, v76, v77
	s_nop 0
	v_lshlrev_b32_e32 v77, 16, v78
	v_and_b32_e32 v78, 0xffff0000, v78
	v_lshlrev_b32_e32 v103, 16, v79
	v_and_b32_e32 v79, 0xffff0000, v79
	v_lshlrev_b32_e32 v122, 16, v80
	v_and_b32_e32 v80, 0xffff0000, v80
	v_lshlrev_b32_e32 v123, 16, v74
	v_and_b32_e32 v74, 0xffff0000, v74
	v_lshlrev_b32_e32 v124, 16, v75
	v_and_b32_e32 v75, 0xffff0000, v75
	v_lshlrev_b32_e32 v125, 16, v81
	v_and_b32_e32 v81, 0xffff0000, v81
	v_lshlrev_b32_e32 v136, 16, v102
	v_and_b32_e32 v102, 0xffff0000, v102
	v_lshlrev_b32_e32 v137, 16, v76
	v_and_b32_e32 v76, 0xffff0000, v76
	v_fmac_f32_e32 v119, v98, v77
	v_fmac_f32_e32 v135, v98, v78
	v_fmac_f32_e32 v138, v98, v103
	v_fmac_f32_e32 v139, v98, v79
	v_fmac_f32_e32 v140, v98, v122
	v_fmac_f32_e32 v141, v98, v80
	v_fmac_f32_e32 v142, v98, v123
	v_fmac_f32_e32 v143, v98, v74
	v_fmac_f32_e32 v144, v98, v124
	v_fmac_f32_e32 v145, v98, v75
	v_fmac_f32_e32 v146, v98, v125
	v_fmac_f32_e32 v147, v98, v81
	v_fmac_f32_e32 v148, v98, v136
	v_fmac_f32_e32 v149, v98, v102
	v_fmac_f32_e32 v150, v98, v137
	v_fmac_f32_e32 v151, v98, v76
	v_cvt_pk_bf16_f32 v74, v119, v135
	v_cvt_pk_bf16_f32 v75, v138, v139
	v_cvt_pk_bf16_f32 v76, v140, v141
	v_cvt_pk_bf16_f32 v77, v142, v143
	v_cvt_pk_bf16_f32 v78, v144, v145
	v_cvt_pk_bf16_f32 v79, v146, v147
	v_cvt_pk_bf16_f32 v80, v148, v149
	v_cvt_pk_bf16_f32 v81, v150, v151
	s_waitcnt vmcnt(0)
	v_mov_b32_e32 v100, v220
	v_mov_b32_e32 v101, v221
	v_mov_b32_e32 v102, v222
	v_mov_b32_e32 v103, v223
	v_lshlrev_b32_e32 v119, 16, v90
	v_and_b32_e32 v135, 0xffff0000, v90
	v_lshlrev_b32_e32 v136, 16, v91
	v_and_b32_e32 v137, 0xffff0000, v91
	v_lshlrev_b32_e32 v138, 16, v92
	v_and_b32_e32 v139, 0xffff0000, v92
	v_lshlrev_b32_e32 v140, 16, v93
	v_and_b32_e32 v141, 0xffff0000, v93
	v_lshlrev_b32_e32 v142, 16, v94
	v_and_b32_e32 v143, 0xffff0000, v94
	v_lshlrev_b32_e32 v144, 16, v95
	v_and_b32_e32 v145, 0xffff0000, v95
	v_lshlrev_b32_e32 v146, 16, v96
	v_and_b32_e32 v147, 0xffff0000, v96
	v_lshlrev_b32_e32 v148, 16, v97
	v_and_b32_e32 v149, 0xffff0000, v97
	s_waitcnt vmcnt(0)
	v_cvt_pk_f32_fp8_e32 v[90:91], v100
	v_cvt_pk_f32_fp8_sdwa v[92:93], v100 src0_sel:WORD_1
	v_cvt_pk_f32_fp8_e32 v[94:95], v101
	v_cvt_pk_f32_fp8_sdwa v[96:97], v101 src0_sel:WORD_1
	v_cvt_pk_f32_fp8_e32 v[100:101], v102
	v_cvt_pk_f32_fp8_sdwa v[122:123], v102 src0_sel:WORD_1
	v_cvt_pk_f32_fp8_e32 v[124:125], v103
	v_cvt_pk_f32_fp8_sdwa v[102:103], v103 src0_sel:WORD_1
	v_cvt_pk_bf16_f32 v90, v90, v91
	v_cvt_pk_bf16_f32 v91, v92, v93
	v_cvt_pk_bf16_f32 v92, v94, v95
	v_cvt_pk_bf16_f32 v93, v96, v97
	v_cvt_pk_bf16_f32 v94, v100, v101
	v_cvt_pk_bf16_f32 v95, v122, v123
	v_cvt_pk_bf16_f32 v96, v124, v125
	v_cvt_pk_bf16_f32 v97, v102, v103
	s_nop 0
	v_lshlrev_b32_e32 v100, 16, v90
	v_and_b32_e32 v90, 0xffff0000, v90
	v_lshlrev_b32_e32 v101, 16, v91
	v_and_b32_e32 v91, 0xffff0000, v91
	v_lshlrev_b32_e32 v102, 16, v92
	v_and_b32_e32 v92, 0xffff0000, v92
	v_lshlrev_b32_e32 v103, 16, v93
	v_and_b32_e32 v93, 0xffff0000, v93
	v_lshlrev_b32_e32 v122, 16, v94
	v_and_b32_e32 v94, 0xffff0000, v94
	v_lshlrev_b32_e32 v123, 16, v95
	v_and_b32_e32 v95, 0xffff0000, v95
	v_lshlrev_b32_e32 v124, 16, v96
	v_and_b32_e32 v96, 0xffff0000, v96
	v_lshlrev_b32_e32 v125, 16, v97
	v_and_b32_e32 v97, 0xffff0000, v97
	v_fmac_f32_e32 v119, v98, v100
	v_fmac_f32_e32 v135, v98, v90
	v_fmac_f32_e32 v136, v98, v101
	v_fmac_f32_e32 v137, v98, v91
	v_fmac_f32_e32 v138, v98, v102
	v_fmac_f32_e32 v139, v98, v92
	v_fmac_f32_e32 v140, v98, v103
	v_fmac_f32_e32 v141, v98, v93
	v_fmac_f32_e32 v142, v98, v122
	v_fmac_f32_e32 v143, v98, v94
	v_fmac_f32_e32 v144, v98, v123
	v_fmac_f32_e32 v145, v98, v95
	v_fmac_f32_e32 v146, v98, v124
	v_fmac_f32_e32 v147, v98, v96
	v_fmac_f32_e32 v148, v98, v125
	v_fmac_f32_e32 v149, v98, v97
	v_mul_f32_e32 v98, v99, v98
	v_cvt_pk_bf16_f32 v90, v119, v135
	v_cvt_pk_bf16_f32 v91, v136, v137
	v_cvt_pk_bf16_f32 v92, v138, v139
	v_cvt_pk_bf16_f32 v93, v140, v141
	v_cvt_pk_bf16_f32 v94, v142, v143
	v_cvt_pk_bf16_f32 v95, v144, v145
	v_cvt_pk_bf16_f32 v96, v146, v147
	v_cvt_pk_bf16_f32 v97, v148, v149
	s_cbranch_scc1 .LBB0_390
